# attention O epilogue: 1/l via four ds_read_b128, bf16 tile transposed through the idle LDS ring, four 16-byte stores per lane instead of 32 two-byte stores
# speedup vs baseline: 1.0010x; 1.0002x over previous
; DEV unsigned cvt_pk_bf16(float lo, float hi) { unsigned r; asm volatile("v_cvt_pk_bf16_f32 %0, %1, %2" : "=v"(r) : "v"(lo), "v"(hi)); return r; }
; DEV int crow(int r, int hi) { return (r & 3) + 8 * (r >> 2) + 4 * hi; }
; DEV void attn_unit(int b, int h, int qb, const bf16_t* Q, const bf16_t* K, const bf16_t* V, bf16_t* O, LAS unsigned char* sh, const int tid, const float* qgain) {
;     ...
;     lsum += __shfl_xor(lsum, 32);
;     if (hi == 0) wsf[r32] = 1.0f / lsum;
;     asm volatile("s_waitcnt lgkmcnt(0)" ::: "memory");
;     bf16_t* Ow = O + qrow0 * 1024 + h * 64;
; #pragma unroll
;     for (int r = 0; r < 16; ++r) { const int q = crow(r, hi); const float f = wsf[q];
;         const unsigned a = cvt_pk_bf16(o[0][r] * f, o[1][r] * f);
;         Ow[(long)q * 1024 + r32] = (bf16_t)(a & 0xffffu); Ow[(long)q * 1024 + 32 + r32] = (bf16_t)(a >> 16); }
;     __syncthreads();
.LBB0_2102:
	s_or_b64 exec, exec, s[4:5]
	s_waitcnt lgkmcnt(0)
	v_add_u32_e32 v34, s33, v191
	s_lshl_b64 s[4:5], s[6:7], 11
	v_readlane_b32 s6, v251, 39
	v_readlane_b32 s7, v251, 40
	ds_read_b128 v[36:39], v34 offset:40960
	ds_read_b128 v[40:43], v34 offset:40992
	ds_read_b128 v[44:47], v34 offset:41024
	ds_read_b128 v[48:51], v34 offset:41056
	s_add_u32 s4, s6, s4
	s_addc_u32 s5, s7, s5
	s_add_u32 s4, s4, s10
	s_addc_u32 s5, s5, 0
	s_mov_b64 s[12:13], s[4:5]
	s_mul_i32 s14, s33, 18
	v_mul_u32_u24_e32 v53, 36, v191
	v_lshl_add_u32 v53, v132, 1, v53
	v_add_u32_e32 v53, s14, v53
	v_lshrrev_b32_e32 v54, 3, v130
	v_and_b32_e32 v55, 7, v130
	v_mul_u32_u24_e32 v56, 144, v54
	v_lshl_add_u32 v56, v55, 4, v56
	v_add_u32_e32 v56, s14, v56
	v_lshlrev_b32_e32 v57, 11, v54
	v_lshl_add_u32 v57, v55, 4, v57
	s_waitcnt lgkmcnt(0)
	v_mul_f32_e32 v0, v0, v36
	v_mul_f32_e32 v16, v16, v36
	v_cvt_pk_bf16_f32 v0, v0, v16
	v_mul_f32_e32 v1, v1, v37
	v_mul_f32_e32 v17, v17, v37
	v_cvt_pk_bf16_f32 v1, v1, v17
	v_mul_f32_e32 v2, v2, v38
	v_mul_f32_e32 v18, v18, v38
	v_cvt_pk_bf16_f32 v2, v2, v18
	v_mul_f32_e32 v3, v3, v39
	v_mul_f32_e32 v19, v19, v39
	v_cvt_pk_bf16_f32 v3, v3, v19
	v_mul_f32_e32 v4, v4, v40
	v_mul_f32_e32 v20, v20, v40
	v_cvt_pk_bf16_f32 v4, v4, v20
	v_mul_f32_e32 v5, v5, v41
	v_mul_f32_e32 v21, v21, v41
	v_cvt_pk_bf16_f32 v5, v5, v21
	v_mul_f32_e32 v6, v6, v42
	v_mul_f32_e32 v22, v22, v42
	v_cvt_pk_bf16_f32 v6, v6, v22
	v_mul_f32_e32 v7, v7, v43
	v_mul_f32_e32 v23, v23, v43
	v_cvt_pk_bf16_f32 v7, v7, v23
	v_mul_f32_e32 v8, v8, v44
	v_mul_f32_e32 v24, v24, v44
	v_cvt_pk_bf16_f32 v8, v8, v24
	v_mul_f32_e32 v9, v9, v45
	v_mul_f32_e32 v25, v25, v45
	v_cvt_pk_bf16_f32 v9, v9, v25
	v_mul_f32_e32 v10, v10, v46
	v_mul_f32_e32 v26, v26, v46
	v_cvt_pk_bf16_f32 v10, v10, v26
	v_mul_f32_e32 v11, v11, v47
	v_mul_f32_e32 v27, v27, v47
	v_cvt_pk_bf16_f32 v11, v11, v27
	v_mul_f32_e32 v12, v12, v48
	v_mul_f32_e32 v28, v28, v48
	v_cvt_pk_bf16_f32 v12, v12, v28
	v_mul_f32_e32 v13, v13, v49
	v_mul_f32_e32 v29, v29, v49
	v_cvt_pk_bf16_f32 v13, v13, v29
	v_mul_f32_e32 v14, v14, v50
	v_mul_f32_e32 v30, v30, v50
	v_cvt_pk_bf16_f32 v14, v14, v30
	v_mul_f32_e32 v15, v15, v51
	v_mul_f32_e32 v31, v31, v51
	v_cvt_pk_bf16_f32 v15, v15, v31
	ds_write_b16 v53, v0
	ds_write_b16_d16_hi v53, v0 offset:64
	ds_write_b16 v53, v1 offset:144
	ds_write_b16_d16_hi v53, v1 offset:208
	ds_write_b16 v53, v2 offset:288
	ds_write_b16_d16_hi v53, v2 offset:352
	ds_write_b16 v53, v3 offset:432
	ds_write_b16_d16_hi v53, v3 offset:496
	ds_write_b16 v53, v4 offset:1152
	ds_write_b16_d16_hi v53, v4 offset:1216
	ds_write_b16 v53, v5 offset:1296
	ds_write_b16_d16_hi v53, v5 offset:1360
	ds_write_b16 v53, v6 offset:1440
	ds_write_b16_d16_hi v53, v6 offset:1504
	ds_write_b16 v53, v7 offset:1584
	ds_write_b16_d16_hi v53, v7 offset:1648
	ds_write_b16 v53, v8 offset:2304
	ds_write_b16_d16_hi v53, v8 offset:2368
	ds_write_b16 v53, v9 offset:2448
	ds_write_b16_d16_hi v53, v9 offset:2512
	ds_write_b16 v53, v10 offset:2592
	ds_write_b16_d16_hi v53, v10 offset:2656
	ds_write_b16 v53, v11 offset:2736
	ds_write_b16_d16_hi v53, v11 offset:2800
	ds_write_b16 v53, v12 offset:3456
	ds_write_b16_d16_hi v53, v12 offset:3520
	ds_write_b16 v53, v13 offset:3600
	ds_write_b16_d16_hi v53, v13 offset:3664
	ds_write_b16 v53, v14 offset:3744
	ds_write_b16_d16_hi v53, v14 offset:3808
	ds_write_b16 v53, v15 offset:3888
	ds_write_b16_d16_hi v53, v15 offset:3952
	s_add_i32 s31, s31, 1
	v_readlane_b32 s4, v251, 19
	s_waitcnt lgkmcnt(0)
	ds_read_b128 v[60:63], v56
	ds_read_b128 v[64:67], v56 offset:1152
	ds_read_b128 v[68:71], v56 offset:2304
	ds_read_b128 v[72:75], v56 offset:3456
	s_cmp_eq_u32 s31, s4
	s_cselect_b64 s[4:5], -1, 0
	v_add_u32_e32 v58, 0x4000, v57
	v_add_u32_e32 v59, 0x8000, v57
	v_add_u32_e32 v76, 0xc000, v57
	s_waitcnt lgkmcnt(0)
	global_store_dwordx4 v57, v[60:63], s[12:13]
	global_store_dwordx4 v58, v[64:67], s[12:13]
	global_store_dwordx4 v59, v[68:71], s[12:13]
	global_store_dwordx4 v76, v[72:75], s[12:13]
	s_barrier
